# GDN scan: all three unrolled steps stage the next chunk's LDS writes under the previous step's MFMAs (first chunk staged in the set-up)
# baseline (speedup 1.0000x reference)
; DI int otid() { int t = threadIdx.x; asm volatile("" : "+v"(t)); return t; }
; DI void gdn_scan_item(const P& p, int item, unsigned char* smem) {
;     ...
;     const int tid = otid(), w = tid >> 6, lane = tid & 63, l15 = lane & 15, g = lane >> 4, q4 = l15 >> 2, p4 = l15 & 3;
;     const int mt = w >> 1, nt = w & 1;
;     auto loadr = [&](GdnRegs& R, int c) {
;         if (c >= 36) return;
;         u32x4* rr = R.r;
; #pragma unroll
;         for (int k = 0; k < 2; ++k) {
;             const int e = tid + 512 * k, r = e >> 4, ch = e & 15; const size_t off = ((size_t)seq * PT + 64 * c + r) * 128 + 8 * ch;
;             rr[k] = *(const u32x4*)(W + off); rr[2 + k] = *(const u32x4*)(QI + off); rr[4 + k] = *(const u32x4*)(KO + off);
;         }
;         { const int r = tid >> 3, ch = tid & 7; rr[6] = *(const u32x4*)(AT + (((size_t)seq * 36 + c) * 64 + r) * 64 + 8 * ch); }
;         if (tid < 256) { const int r = tid >> 2, ch = tid & 3; rr[7] = __builtin_nontemporal_load((const u32x4*)(U + ((size_t)seq * PT + 64 * c + r) * 128 + 32 * cq + 8 * ch)); }
;     };
;     auto storel = [&](const GdnRegs& R, int buf) {
;         const u32x4* rr = R.r;
;         bf16_t* sW = (bf16_t*)(smem + buf * BUFB); bf16_t* sQI = sW + 64 * 136; bf16_t* sKO = sQI + 64 * 136; bf16_t* sAT = sKO + 64 * 136; bf16_t* sU = sAT + 64 * 72;
; #pragma unroll
;         for (int k = 0; k < 2; ++k) {
;             const int e = tid + 512 * k, r = e >> 4, ch = e & 15; const int off = r * 136 + 8 * ch;
;             *(u32x4*)(sW + off) = rr[k]; *(u32x4*)(sQI + off) = rr[2 + k]; *(u32x4*)(sKO + off) = rr[4 + k];
;         }
;         { const int r = tid >> 3, ch = tid & 7; *(u32x4*)(sAT + r * 72 + 8 * ch) = rr[6]; }
;         if (tid < 256) { const int r = tid >> 2, ch = tid & 3; *(u32x4*)(sU + r * 40 + 8 * ch) = rr[7]; }
;     };
;     u32x4* sBS = (u32x4*)(smem + 2 * BUFB + 5120 + 256);
;     f32x4 st[2];
;     st[0] = (f32x4){0.f, 0.f, 0.f, 0.f}; st[1] = (f32x4){0.f, 0.f, 0.f, 0.f};
;     sBS[(nt * 4 + mt) * 64 + lane] = (u32x4){0u, 0u, 0u, 0u};
;     if (tid < 36) sdec[tid] = DC[seq * 36 + tid];
;     const int sgn = dir ? -1 : 1;
.LBB0_499:
	s_or_b64 exec, exec, s[38:39]
	s_lshr_b32 s2, s22, 4
	s_and_b32 s3, s56, 3
	s_add_i32 s6, s57, 0x20800
	s_mul_i32 s2, s2, 0x900000
	s_add_u32 s2, s46, s2
	s_addc_u32 s4, s47, 0
	s_cmp_lt_u32 s22, 16
	s_cselect_b64 s[38:39], -1, 0
	s_lshl_b32 s5, s24, 8
	s_add_u32 s7, s2, s5
	s_movk_i32 s9, 0x88
	s_addc_u32 s8, s4, 0
	v_mad_u64_u32 v[120:121], s[4:5], v98, s9, v[132:133]
	v_mad_u64_u32 v[122:123], s[4:5], v100, s9, v[132:133]
	v_and_b32_e32 v108, 15, v96
	s_movk_i32 s4, 0x48
	v_lshrrev_b32_e32 v112, 4, v110
	v_mul_lo_u32 v114, v106, s4
	v_lshl_add_u32 v117, v110, 4, v111
	v_lshl_or_b32 v110, v97, 4, v108
	s_movk_i32 s4, 0x50
	v_lshlrev_b32_e32 v132, 5, v105
	v_lshlrev_b32_e32 v115, 4, v105
	v_mul_lo_u32 v106, v110, s4
	v_lshlrev_b32_e32 v124, 3, v112
	v_add_u32_e32 v105, s6, v132
	v_add3_u32 v123, v105, v106, v124
	v_lshlrev_b32_e32 v106, 2, v96
	v_bfe_u32 v113, v96, 2, 2
	v_and_b32_e32 v157, 12, v106
	v_lshlrev_b32_e32 v107, 13, v97
	v_lshlrev_b32_e32 v111, 2, v112
	v_lshl_add_u32 v112, v157, 1, v105
	v_or_b32_e32 v105, 4, v113
	v_lshl_or_b32 v107, v108, 9, v107
	s_lshl_b32 s2, s3, 11
	s_lshl_b32 s3, s3, 8
	v_or_b32_e32 v106, v124, v105
	v_sub_u32_e32 v109, 0, v107
	s_bitset1_b32 s3, 13
	v_mul_u32_u24_e32 v150, 0x50, v106
	v_or_b32_e32 v106, 32, v124
	v_or_b32_e32 v134, v124, v113
	v_or_b32_e32 v113, v106, v113
	v_or_b32_e32 v105, v106, v105
	s_add_u32 s4, s7, s26
	v_cndmask_b32_e64 v106, v109, v107, s[38:39]
	s_addc_u32 s5, s8, 0
	v_ashrrev_i32_e32 v107, 31, v106
	v_lshl_add_u64 v[106:107], v[106:107], 1, s[4:5]
	v_lshl_add_u64 v[106:107], v[106:107], 0, v[132:133]
	v_mov_b32_e32 v125, v133
	v_lshl_add_u64 v[106:107], v[106:107], 0, v[124:125]
	s_mov_b64 s[4:5], 0x5a3c000
	v_lshl_add_u64 v[126:127], v[106:107], 0, s[4:5]
	s_movk_i32 s4, 0xff40
	v_mul_lo_u32 v158, v110, s4
	s_movk_i32 s4, 0xc0
	s_add_i32 s24, s24, s22
	v_and_b32_e32 v96, 7, v96
	v_mul_lo_u32 v121, v110, s9
	v_lshlrev_b32_e32 v125, 5, v97
	v_mul_lo_u32 v159, v110, s4
	v_lshlrev_b32_e32 v97, 7, v110
	v_mad_u64_u32 v[102:103], s[4:5], s24, v181, v[102:103]
	v_lshlrev_b32_e32 v132, 4, v96
	v_readlane_b32 s8, v254, 26
	v_mul_u32_u24_e32 v152, 0x50, v105
	v_ashrrev_i32_e32 v105, 31, v104
	v_sub_u32_e32 v160, 0, v97
	v_lshl_add_u64 v[96:97], v[102:103], 0, v[132:133]
	v_readlane_b32 s9, v254, 27
	v_mul_u32_u24_e32 v135, 0x50, v134
	v_mul_u32_u24_e32 v151, 0x50, v113
	v_lshl_add_u64 v[142:143], s[8:9], 0, v[96:97]
	v_lshlrev_b64 v[96:97], 8, v[104:105]
	v_mad_u64_u32 v[96:97], s[4:5], s24, v182, v[96:97]
	s_lshl_b32 s4, s56, 3
	s_and_b32 s4, s4, 0xc0
	v_or_b32_e32 v96, s4, v96
	v_lshl_add_u64 v[96:97], v[118:119], 1, v[96:97]
	v_lshl_add_u64 v[144:145], s[8:9], 0, v[96:97]
	v_lshlrev_b64 v[96:97], 8, v[100:101]
	v_mad_u64_u32 v[96:97], s[4:5], s24, v182, v[96:97]
	v_lshlrev_b32_e32 v100, 4, v108
	v_or_b32_e32 v96, v96, v100
	v_lshl_add_u64 v[146:147], s[8:9], 0, v[96:97]
	v_lshlrev_b64 v[96:97], 8, v[98:99]
	v_mad_u64_u32 v[96:97], s[4:5], s24, v182, v[96:97]
	v_or_b32_e32 v96, v96, v100
	v_mul_u32_u24_e32 v106, 0x88, v134
	v_mul_u32_u24_e32 v107, 0x88, v113
	v_mul_lo_u32 v109, v104, 40
	v_lshl_add_u64 v[148:149], s[8:9], 0, v[96:97]
	v_mov_b32_e32 v96, 0
	s_mov_b32 s27, -3
	s_movk_i32 s22, 0x80
	s_movk_i32 s24, 0x87f
	v_lshlrev_b32_e32 v119, 1, v114
	v_lshlrev_b32_e32 v161, 1, v109
	v_lshlrev_b32_e32 v162, 1, v111
	v_lshlrev_b32_e32 v163, 1, v115
	v_add_u32_e32 v164, v112, v135
	v_add_u32_e32 v165, v112, v150
	v_add_u32_e32 v183, v112, v151
	v_add_u32_e32 v184, v112, v152
	v_lshlrev_b32_e32 v185, 1, v106
	v_lshlrev_b32_e32 v186, 1, v107
	v_mov_b32_e32 v97, v96
	v_mov_b32_e32 v98, v96
	v_mov_b32_e32 v99, v96
	v_mov_b32_e32 v100, v96
	v_mov_b32_e32 v101, v96
	v_mov_b32_e32 v102, v96
	v_mov_b32_e32 v103, v96
	v_readlane_b32 s10, v254, 28
	v_readlane_b32 s11, v254, 29
	v_cmp_gt_i32_e64 s[98:99], 36, v166
	s_nop 1
	s_and_saveexec_b64 s[100:101], s[98:99]
	s_waitcnt vmcnt(20)
	ds_write_b32 v217, v216
	s_mov_b64 exec, s[100:101]
	v_lshl_add_u32 v213, v120, 1, s57
	v_lshl_add_u32 v214, v122, 1, s57
	v_add3_u32 v215, s57, v119, v116
	s_waitcnt vmcnt(20)
	ds_write_b128 v213, v[0:3]
	s_waitcnt vmcnt(19)
	ds_write_b128 v213, v[4:7] offset:17408
	s_waitcnt vmcnt(18)
	ds_write_b128 v213, v[8:11] offset:34816
	s_waitcnt vmcnt(17)
	ds_write_b128 v214, v[12:15]
	s_waitcnt vmcnt(16)
	ds_write_b128 v214, v[16:19] offset:17408
	s_waitcnt vmcnt(15)
	ds_write_b128 v214, v[24:27] offset:34816
	s_waitcnt vmcnt(14)
	ds_write_b128 v215, v[36:39] offset:52224
	s_branch .LBB0_501
; DI float lo16(unsigned u) { return __uint_as_float(u << 16); }
; DI void gdn_scan_item(const P& p, int item, unsigned char* smem) {
;     ...
;     auto step = [&](GdnRegs& R, int c) {
;         storel(R, c & 1);
;         __syncthreads();
;         loadr(R, c + 3);
;         const bf16_t* sW = (const bf16_t*)(smem + (c & 1) * BUFB); const bf16_t* sQI = sW + 64 * 136; const bf16_t* sKO = sQI + 64 * 136; const bf16_t* sAT = sKO + 64 * 136; const bf16_t* sU = sAT + 64 * 72;
;         const float dec = sdec[c];
;         bf16x8 Bs[4];
; #pragma unroll
;         for (int ks = 0; ks < 4; ++ks) Bs[ks] = __builtin_bit_cast(bf16x8, sBS[(nt * 4 + ks) * 64 + lane]);
;         {
;             f32x4 acc = (f32x4){0.f, 0.f, 0.f, 0.f};
; #pragma unroll
;             for (int ks = 0; ks < 4; ++ks) { const bf16_t* r0 = sW + (16 * mt + l15) * 136 + 32 * ks + 4 * g; acc = mfma16(Bs[ks], ld4x2(r0, r0 + 16), acc); }
;             {
;                 const u32x2 uu = *(const u32x2*)(sU + (16 * mt + l15) * 40 + 16 * nt + 4 * g);
;                 u32x2 vv; vv.x = pk2(lo16(uu.x) - acc[0], hi16(uu.x) - acc[1]); vv.y = pk2(lo16(uu.y) - acc[2], hi16(uu.y) - acc[3]);
;                 *(u32x2*)(sVN + (16 * mt + l15) * 40 + 16 * nt + 4 * g) = vv;
;             }
;         }
;         __syncthreads();
;         bf16x8 Bv[2];
; #pragma unroll
;         for (int k2 = 0; k2 < 2; ++k2) Bv[k2] = tr2(sVN + (32 * k2 + 8 * g + q4) * 40 + 16 * nt + 4 * p4, sVN + (32 * k2 + 8 * g + 4 + q4) * 40 + 16 * nt + 4 * p4);
;         {
;             f32x4 acc = (f32x4){0.f, 0.f, 0.f, 0.f};
; #pragma unroll
;             for (int ks = 0; ks < 4; ++ks) { const bf16_t* r0 = sQI + (16 * mt + l15) * 136 + 32 * ks + 4 * g; acc = mfma16(Bs[ks], ld4x2(r0, r0 + 16), acc); }
; #pragma unroll
;             for (int k2 = 0; k2 < 2; ++k2) acc = mfma16(Bv[k2], ld8(sAT + (16 * mt + l15) * 72 + 32 * k2 + 8 * g), acc);
;             bf16_t* ob = OG + (size_t)prow(b, dir, 64 * c) * 512 + 128 * h + 32 * cq;
;             u32x2 ov; ov.x = pk2(acc[0], acc[1]); ov.y = pk2(acc[2], acc[3]);
;             *(u32x2*)(ob + sgn * ((16 * mt + l15) * 512) + 16 * nt + 4 * g) = ov;
;         }
; #pragma unroll
;         for (int j = 0; j < 2; ++j) {
;             const int dt = 2 * mt + j;
;             st[j] *= dec;
; #pragma unroll
;             for (int k2 = 0; k2 < 2; ++k2) {
.LBB0_500:
	ds_read_b64_tr_b16 v[226:227], v187 offset:35904
	ds_read_b64_tr_b16 v[224:225], v187 offset:34816
	ds_read_b64_tr_b16 v[228:229], v187 offset:34848
	ds_read_b64_tr_b16 v[232:233], v193 offset:34848
	ds_read_b64_tr_b16 v[230:231], v187 offset:35936
	ds_read_b64_tr_b16 v[234:235], v187 offset:44640
	s_ashr_i32 s43, s42, 31
	s_lshl_b64 s[4:5], s[42:43], 10
	s_nop 2
	v_cvt_pk_bf16_f32 v112, v112, v113
	v_cvt_pk_bf16_f32 v113, v114, v115
	v_lshl_add_u64 v[114:115], v[126:127], 0, s[4:5]
	global_store_dwordx2 v[114:115], v[112:113], off
	ds_read_b64_tr_b16 v[114:115], v187 offset:44608
	ds_read_b64_tr_b16 v[112:113], v193 offset:34816
	v_pk_mul_f32 v[98:99], v[98:99], v[132:133] op_sel_hi:[1,0]
	v_pk_mul_f32 v[96:97], v[96:97], v[132:133] op_sel_hi:[1,0]
	v_pk_mul_f32 v[102:103], v[102:103], v[132:133] op_sel_hi:[1,0]
	v_pk_mul_f32 v[100:101], v[100:101], v[132:133] op_sel_hi:[1,0]
	s_waitcnt lgkmcnt(6)
	v_mfma_f32_16x16x32_bf16 v[96:99], v[224:227], v[108:111], v[96:99]
	s_waitcnt vmcnt(15)
	ds_write_b128 v214, v[24:27] offset:34816
	s_waitcnt lgkmcnt(1)
	v_mfma_f32_16x16x32_bf16 v[96:99], v[112:115], v[104:107], v[96:99]
	s_waitcnt vmcnt(14)
	ds_write_b128 v215, v[36:39] offset:52224
	s_mov_b64 s[4:5], 0x6000
	v_lshl_add_u64 v[142:143], v[142:143], 0, s[4:5]
	s_mov_b64 s[4:5], 0xc000
	v_mfma_f32_16x16x32_bf16 v[100:103], v[228:231], v[108:111], v[100:103]
	s_add_i32 s21, s21, 12
	s_addk_i32 s22, 0xc0
	s_addk_i32 s24, 0xff40
	v_mfma_f32_16x16x32_bf16 v[100:103], v[232:235], v[104:107], v[100:103]
	v_cvt_pk_bf16_f32 v104, v96, v97
	v_cvt_pk_bf16_f32 v105, v98, v99
	v_lshl_add_u64 v[144:145], v[144:145], 0, s[4:5]
	v_lshl_add_u64 v[146:147], v[146:147], 0, s[4:5]
	v_lshl_add_u64 v[148:149], v[148:149], 0, s[4:5]
	s_nop 2
	v_cvt_pk_bf16_f32 v106, v100, v101
	v_cvt_pk_bf16_f32 v107, v102, v103
	s_cmp_lt_u32 s26, 33
	s_mov_b32 s27, s26
	ds_write_b128 v156, v[104:107]
	s_waitcnt lgkmcnt(0)
	s_cbranch_scc0 .LBB0_640
.LBB0_501:
	s_add_i32 s26, s27, 3
	s_bitcmp1_b32 s26, 0
	s_cselect_b32 s4, 0x10400, 0
	s_add_i32 s28, s57, s4
	v_lshlrev_b32_e32 v198, 1, v118
	v_lshl_add_u32 v190, v120, 1, s28
	v_lshl_add_u32 v192, v122, 1, s28
	v_add3_u32 v194, s28, v119, v116
	v_add3_u32 v191, s28, v161, v198
	s_waitcnt vmcnt(14)
	s_and_saveexec_b64 s[40:41], s[0:1]
	ds_write_b128 v191, v[20:23] offset:61440
	s_or_b64 exec, exec, s[40:41]
	s_cmp_gt_u32 s26, 32
	v_lshl_add_u64 v[154:155], v[148:149], 0, s[44:45]
	v_lshl_add_u64 v[152:153], v[146:147], 0, s[44:45]
	v_lshl_add_u64 v[150:151], v[142:143], 0, s[44:45]
	s_waitcnt lgkmcnt(0)
	s_barrier
	ds_read_b128 v[112:115], v117
	ds_read_b128 v[200:203], v117 offset:1024
	ds_read_b128 v[204:207], v117 offset:2048
	ds_read_b128 v[208:211], v117 offset:3072
	v_lshl_add_u32 v134, v121, 1, s28
	v_mov_b32_e32 v104, s21
	ds_read_b32 v132, v104
	v_add_u32_e32 v188, v134, v162
	ds_read2_b64 v[224:227], v188 offset1:4
	ds_read2_b64 v[228:231], v188 offset0:8 offset1:12
	ds_read2_b64 v[232:235], v188 offset0:16 offset1:20
	ds_read2_b64 v[236:239], v188 offset0:24 offset1:28
	v_add_u32_e32 v134, v134, v158
	s_cbranch_scc1 .LBB0_507
	v_add_co_u32_e32 v0, vcc, 0x13f58000, v154
	s_nop 1
	v_addc_co_u32_e32 v1, vcc, 0, v155, vcc
	v_add_co_u32_e32 v4, vcc, 0x15158000, v154
	s_nop 1
	v_addc_co_u32_e32 v5, vcc, 0, v155, vcc
	v_add_co_u32_e32 v8, vcc, 0x16358000, v154
	global_load_dwordx4 v[0:3], v[0:1], off
	s_nop 0
	global_load_dwordx4 v[4:7], v[4:5], off
	v_addc_co_u32_e32 v9, vcc, 0, v155, vcc
	v_add_co_u32_e32 v12, vcc, 0x13f58000, v152
	global_load_dwordx4 v[8:11], v[8:9], off
	s_nop 0
	v_addc_co_u32_e32 v13, vcc, 0, v153, vcc
	v_add_co_u32_e32 v16, vcc, 0x15158000, v152
	s_nop 1
	v_addc_co_u32_e32 v17, vcc, 0, v153, vcc
	v_add_co_u32_e32 v24, vcc, 0x16358000, v152
	global_load_dwordx4 v[12:15], v[12:13], off
	s_nop 0
	global_load_dwordx4 v[16:19], v[16:17], off
	v_addc_co_u32_e32 v25, vcc, 0, v153, vcc
	v_add_co_u32_e32 v36, vcc, 0x17552000, v150
	global_load_dwordx4 v[24:27], v[24:25], off
	s_nop 0
	v_addc_co_u32_e32 v37, vcc, 0, v151, vcc
	global_load_dwordx4 v[36:39], v[36:37], off
	s_and_saveexec_b64 s[40:41], s[0:1]
	s_cbranch_execz .LBB0_506
	v_lshl_add_u64 v[20:21], v[144:145], 0, s[44:45]
	v_add_co_u32_e32 v20, vcc, 0x12d58000, v20
	s_nop 1
	v_addc_co_u32_e32 v21, vcc, 0, v21, vcc
	global_load_dwordx4 v[20:23], v[20:21], off nt

; DI float lo16(unsigned u) { return __uint_as_float(u << 16); }
; DI void gdn_scan_item(const P& p, int item, unsigned char* smem) {
;     ...
;     auto storel = [&](const GdnRegs& R, int buf) {
;         const u32x4* rr = R.r;
;         bf16_t* sW = (bf16_t*)(smem + buf * BUFB); bf16_t* sQI = sW + 64 * 136; bf16_t* sKO = sQI + 64 * 136; bf16_t* sAT = sKO + 64 * 136; bf16_t* sU = sAT + 64 * 72;
; #pragma unroll
;         for (int k = 0; k < 2; ++k) {
;             const int e = tid + 512 * k, r = e >> 4, ch = e & 15; const int off = r * 136 + 8 * ch;
;             *(u32x4*)(sW + off) = rr[k]; *(u32x4*)(sQI + off) = rr[2 + k]; *(u32x4*)(sKO + off) = rr[4 + k];
;         }
;         { const int r = tid >> 3, ch = tid & 7; *(u32x4*)(sAT + r * 72 + 8 * ch) = rr[6]; }
;         if (tid < 256) { const int r = tid >> 2, ch = tid & 3; *(u32x4*)(sU + r * 40 + 8 * ch) = rr[7]; }
;     ...
;         {
;             f32x4 acc = (f32x4){0.f, 0.f, 0.f, 0.f};
; #pragma unroll
;             for (int ks = 0; ks < 4; ++ks) { const bf16_t* r0 = sW + (16 * mt + l15) * 136 + 32 * ks + 4 * g; acc = mfma16(Bs[ks], ld4x2(r0, r0 + 16), acc); }
;             {
;                 const u32x2 uu = *(const u32x2*)(sU + (16 * mt + l15) * 40 + 16 * nt + 4 * g);
;                 u32x2 vv; vv.x = pk2(lo16(uu.x) - acc[0], hi16(uu.x) - acc[1]); vv.y = pk2(lo16(uu.y) - acc[2], hi16(uu.y) - acc[3]);
;                 *(u32x2*)(sVN + (16 * mt + l15) * 40 + 16 * nt + 4 * g) = vv;
;             }
;         }
;         __syncthreads();
;         bf16x8 Bv[2];
; #pragma unroll
;         for (int k2 = 0; k2 < 2; ++k2) Bv[k2] = tr2(sVN + (32 * k2 + 8 * g + q4) * 40 + 16 * nt + 4 * p4, sVN + (32 * k2 + 8 * g + 4 + q4) * 40 + 16 * nt + 4 * p4);
;         {
;             f32x4 acc = (f32x4){0.f, 0.f, 0.f, 0.f};
; #pragma unroll
;             for (int ks = 0; ks < 4; ++ks) { const bf16_t* r0 = sQI + (16 * mt + l15) * 136 + 32 * ks + 4 * g; acc = mfma16(Bs[ks], ld4x2(r0, r0 + 16), acc); }
; #pragma unroll
;             for (int k2 = 0; k2 < 2; ++k2) acc = mfma16(Bv[k2], ld8(sAT + (16 * mt + l15) * 72 + 32 * k2 + 8 * g), acc);
;             bf16_t* ob = OG + (size_t)prow(b, dir, 64 * c) * 512 + 128 * h + 32 * cq;
;             u32x2 ov; ov.x = pk2(acc[0], acc[1]); ov.y = pk2(acc[2], acc[3]);
;             *(u32x2*)(ob + sgn * ((16 * mt + l15) * 512) + 16 * nt + 4 * g) = ov;
;         }
.LBB0_523:
	s_mov_b64 s[40:41], -1
	s_cmp_gt_u32 s26, 1
	s_waitcnt lgkmcnt(5)
	v_mfma_f32_16x16x32_bf16 v[104:107], v[112:115], v[224:227], 0
	s_waitcnt lgkmcnt(4)
	v_mfma_f32_16x16x32_bf16 v[104:107], v[248:251], v[228:231], v[104:107]
	s_waitcnt lgkmcnt(3)
	v_mfma_f32_16x16x32_bf16 v[104:107], v[198:201], v[232:235], v[104:107]
	s_waitcnt lgkmcnt(2)
	v_mfma_f32_16x16x32_bf16 v[104:107], v[202:205], v[236:239], v[104:107]
	s_waitcnt lgkmcnt(1)
	v_lshlrev_b32_e32 v110, 16, v240
	v_and_b32_e32 v108, 0xffff0000, v240
	s_nop 3
	s_nop 0
	v_sub_f32_e32 v104, v110, v104
	v_sub_f32_e32 v105, v108, v105
	v_cvt_pk_bf16_f32 v104, v104, v105
	v_lshlrev_b32_e32 v105, 16, v241
	v_sub_f32_e32 v105, v105, v106
	v_and_b32_e32 v106, 0xffff0000, v241
	v_sub_f32_e32 v106, v106, v107
	v_cvt_pk_bf16_f32 v105, v105, v106
	ds_write_b64 v123, v[104:105]
	s_waitcnt lgkmcnt(0)
	s_barrier
	v_mov_b32_e32 v212, s57
	v_add_u32_e32 v212, s57, v212
	v_add_u32_e32 v212, 0x10400, v212
	v_subrev_u32_e32 v212, s28, v212
	v_lshl_add_u32 v213, v120, 1, v212
	v_lshl_add_u32 v214, v122, 1, v212
	v_add3_u32 v215, v212, v119, v116
	ds_read_b64_tr_b16 v[108:109], v164
	ds_read_b64_tr_b16 v[110:111], v165
	ds_read_b64_tr_b16 v[104:105], v183
	ds_read_b64_tr_b16 v[106:107], v184
	ds_read2_b64 v[224:227], v189 offset0:128 offset1:132
	ds_read2_b64 v[228:231], v189 offset0:136 offset1:140
	ds_read2_b64 v[232:235], v189 offset0:144 offset1:148
	ds_read2_b64 v[236:239], v189 offset0:152 offset1:156
	ds_read_b128 v[240:243], v196 offset:52224
	ds_read_b128 v[244:247], v196 offset:52288
	s_waitcnt lgkmcnt(5)
	v_mfma_f32_16x16x32_bf16 v[112:115], v[112:115], v[224:227], 0
	s_waitcnt vmcnt(20)
	ds_write_b128 v213, v[0:3]
	s_waitcnt lgkmcnt(5)
	v_mfma_f32_16x16x32_bf16 v[112:115], v[248:251], v[228:231], v[112:115]
	s_waitcnt vmcnt(19)
	ds_write_b128 v213, v[4:7] offset:17408
	s_waitcnt lgkmcnt(5)
	v_mfma_f32_16x16x32_bf16 v[112:115], v[198:201], v[232:235], v[112:115]
	s_waitcnt vmcnt(18)
	ds_write_b128 v213, v[8:11] offset:34816
	s_waitcnt lgkmcnt(5)
	v_mfma_f32_16x16x32_bf16 v[112:115], v[202:205], v[236:239], v[112:115]
	s_waitcnt vmcnt(17)
	ds_write_b128 v214, v[12:15]
	s_waitcnt lgkmcnt(5)
	v_mfma_f32_16x16x32_bf16 v[112:115], v[108:111], v[240:243], v[112:115]
	s_waitcnt vmcnt(16)
	ds_write_b128 v214, v[16:19] offset:17408
	s_waitcnt lgkmcnt(5)
	v_mfma_f32_16x16x32_bf16 v[112:115], v[104:107], v[244:247], v[112:115]
	s_cbranch_scc0 .LBB0_525
	s_add_i32 s6, s22, 0xffffff00
	s_and_b64 s[4:5], s[38:39], exec
	s_cselect_b32 s4, s6, s24
	s_add_i32 s42, s4, s2
	s_mov_b64 s[40:41], 0
